# y1 + retention: static s_setprio 1 for waves 4-7 for the whole phase (one raise at entry, reset at exit)
# baseline (speedup 1.0000x reference)
.LBB0_431:
	s_andn2_b64 vcc, exec, s[16:17]
	s_cbranch_vccnz .LBB0_490
	v_readlane_b32 s4, v253, 46
	v_mov_b32_e32 v2, v238
	v_readlane_b32 s5, v253, 47
	s_andn2_b64 vcc, exec, s[4:5]
	v_readfirstlane_b32 s11, v2
	s_cbranch_vccnz .LBB0_440
	s_lshr_b32 s100, s11, 8
	s_cmp_eq_u32 s100, 1
	s_cbranch_scc0 Lret_prio_skip
	s_setprio 1
Lret_prio_skip:
	s_add_u32 s16, s78, 0x41a00000
	s_addc_u32 s17, s79, 0
	s_add_u32 s18, s78, 0x45a00000
	s_addc_u32 s19, s79, 0
	s_add_u32 s20, s78, 0x49a00000
	s_addc_u32 s21, s79, 0
	s_add_u32 s7, s78, 0x59a00000
	s_addc_u32 s10, s79, 0
	s_movk_i32 s12, 0x840
	v_ashrrev_i32_e32 v78, 3, v2
	s_waitcnt lgkmcnt(0)
	v_and_b32_e32 v6, 7, v2
	s_ashr_i32 s13, s11, 3
	v_cmp_gt_i32_e32 vcc, s12, v2
	v_lshlrev_b32_e32 v4, 3, v6
	v_lshlrev_b32_e32 v12, 4, v6
	v_sub_u32_e32 v6, 63, v78
	s_lshr_b32 s12, s11, 5
	v_bfi_b32 v13, -16, s13, v2
	s_movk_i32 s8, 0x210
	v_bfe_u32 v3, v2, 4, 2
	v_cvt_f32_i32_e32 v91, v6
	s_and_b32 s12, s12, 2
	v_mul_lo_u32 v6, v13, s8
	v_and_b32_e32 v1, 15, v2
	s_and_b32 s14, s13, -16
	v_add_u32_e32 v14, 0, v6
	s_lshl_b32 s15, s12, 4
	v_lshlrev_b32_e32 v6, 2, v3
	v_or_b32_e32 v16, s15, v1
	v_or_b32_e32 v18, s14, v6
	v_sub_u32_e32 v27, v18, v16
	v_sub_u32_e32 v28, 0, v27
	v_or_b32_e32 v19, 16, v16
	v_max_i32_e32 v27, v27, v28
	v_cvt_f32_u32_e32 v129, v27
	v_sub_u32_e32 v27, v18, v19
	v_sub_u32_e32 v28, 0, v27
	s_movk_i32 s4, 0x90
	v_max_i32_e32 v27, v27, v28
	v_readlane_b32 s36, v254, 19
	v_cvt_f32_u32_e32 v130, v27
	v_mul_lo_u32 v27, v18, s4
	v_add_u32_e32 v131, s36, v27
	v_or_b32_e32 v27, 1, v18
	v_sub_u32_e32 v28, v27, v16
	v_sub_u32_e32 v29, 0, v28
	v_max_i32_e32 v28, v28, v29
	v_sub_u32_e32 v27, v27, v19
	v_cvt_f32_u32_e32 v132, v28
	v_sub_u32_e32 v28, 0, v27
	v_max_i32_e32 v27, v27, v28
	v_cvt_f32_u32_e32 v133, v27
	v_or_b32_e32 v27, 2, v18
	v_sub_u32_e32 v28, v27, v16
	v_sub_u32_e32 v29, 0, v28
	v_readlane_b32 s9, v254, 18
	v_max_i32_e32 v28, v28, v29
	v_sub_u32_e32 v27, v27, v19
	v_mov_b32_e32 v20, s9
	v_cvt_f32_u32_e32 v135, v28
	v_sub_u32_e32 v28, 0, v27
	v_or_b32_e32 v18, 3, v18
	v_mad_u32_u24 v17, v16, s8, 0
	v_lshlrev_b32_e32 v126, 1, v16
	v_mad_u32_u24 v20, v16, s8, v20
	v_max_i32_e32 v27, v27, v28
	v_sub_u32_e32 v16, v18, v16
	v_cvt_f32_u32_e32 v136, v27
	v_sub_u32_e32 v27, 0, v16
	v_max_i32_e32 v16, v16, v27
	v_cvt_f32_u32_e32 v138, v16
	v_sub_u32_e32 v16, v18, v19
	v_add_u32_e32 v21, 1, v13
	v_sub_u32_e32 v18, 0, v16
	v_lshlrev_b32_e32 v5, 3, v2
	v_lshlrev_b32_e32 v15, 4, v3
	v_cvt_f32_i32_e32 v128, v21
	v_bfe_u32 v21, v2, 2, 2
	v_lshlrev_b32_e32 v3, 3, v3
	v_max_i32_e32 v16, v16, v18
	v_and_b32_e32 v7, 0xf8, v5
	v_and_b32_e32 v5, 24, v5
	s_ashr_i32 s22, s14, 31
	v_or_b32_e32 v80, s14, v1
	s_and_b32 s14, s11, 0xffffffc0
	v_cvt_f32_u32_e32 v139, v16
	v_or_b32_e32 v16, v3, v21
	v_mul_lo_u32 v10, v78, s4
	v_mul_lo_u32 v13, v13, s4
	s_lshl_b32 s12, s12, 5
	v_or_b32_e32 v22, s14, v5
	v_mad_u32_u24 v5, v16, s4, v5
	v_readlane_b32 s4, v254, 20
	v_readlane_b32 s5, v254, 16
	v_lshlrev_b32_e32 v127, 1, v19
	s_or_b32 s13, s12, 32
	v_add_u32_e32 v19, s4, v5
	v_add_u32_e32 v18, s5, v5
	v_add_u32_e32 v142, s12, v19
	v_add_u32_e32 v144, s13, v19
	v_add_u32_e32 v19, 0x1200, v5
	v_readlane_b32 s6, v254, 17
	v_add_u32_e32 v13, s36, v13
	v_mov_b32_e32 v81, s22
	v_add_u32_e32 v141, s12, v18
	v_add_u32_e32 v143, s13, v18
	v_or_b32_e32 v18, 32, v16
	v_add_u32_e32 v21, s5, v19
	v_add_u32_e32 v27, s4, v19
	v_readlane_b32 s22, v254, 25
	v_readlane_b32 s36, v254, 26
	v_readlane_b32 s37, v254, 27
	v_readlane_b32 s38, v254, 28
	v_readlane_b32 s39, v254, 29
	v_readlane_b32 s40, v254, 30
	v_readlane_b32 s41, v254, 31
	v_add_u32_e32 v145, s12, v21
	v_add_u32_e32 v146, s12, v27
	v_mad_u32_u24 v16, v16, s8, v22
	v_add_u32_e32 v150, s6, v5
	v_readlane_b32 s12, v254, 23
	v_add_u32_e32 v154, s22, v5
	v_add_u32_e32 v155, s36, v5
	v_add_u32_e32 v156, s37, v5
	v_add_u32_e32 v157, s38, v5
	v_add_u32_e32 v158, s39, v5
	v_add_u32_e32 v159, s40, v5
	v_add_u32_e32 v160, s41, v5
	v_mad_u32_u24 v5, v18, s8, v22
	v_add_u32_e32 v11, s5, v10
	v_add_u32_e32 v23, 0x200, v2
	v_add_u32_e32 v147, s13, v21
	v_add_u32_e32 v148, s13, v27
	v_readlane_b32 s4, v254, 21
	v_readlane_b32 s5, v254, 22
	v_add_u32_e32 v152, s12, v16
	v_readlane_b32 s13, v254, 24
	v_add_u32_e32 v164, s12, v5
	s_add_i32 s12, s9, s14
	v_ashrrev_i32_e32 v84, 5, v23
	v_add_u32_e32 v23, 0x400, v2
	v_add_u32_e32 v161, s4, v5
	v_add_u32_e32 v163, s5, v5
	v_add_u32_e32 v165, s13, v5
	v_add_u32_e32 v5, s12, v3
	s_add_i32 s12, s14, 0
	v_ashrrev_i32_e32 v79, 31, v78
	v_lshlrev_b32_e32 v8, 4, v2
	v_ashrrev_i32_e32 v86, 5, v23
	v_add_u32_e32 v23, 0x600, v2
	s_add_i32 s12, s12, 0x10820
	v_and_b32_e32 v9, 0x1f0, v8
	v_ashrrev_i32_e32 v82, 5, v2
	v_ashrrev_i32_e32 v88, 5, v23
	v_add_u32_e32 v149, s4, v16
	v_add_u32_e32 v151, s5, v16
	v_add_u32_e32 v153, s13, v16
	v_add_u32_e32 v16, s12, v3
	v_add_u32_e32 v173, 0xfffffe00, v2
	v_and_or_b32 v90, s11, 64, v3
	v_lshlrev_b64 v[2:3], 13, v[78:79]
	v_add_u32_e32 v9, 0, v9
	v_add_u32_e32 v10, s6, v10
	v_ashrrev_i32_e32 v83, 31, v82
	v_ashrrev_i32_e32 v85, 31, v84
	v_ashrrev_i32_e32 v87, 31, v86
	v_ashrrev_i32_e32 v89, 31, v88
	v_mul_lo_u32 v23, v82, s8
	v_mul_lo_u32 v24, v84, s8
	v_mul_lo_u32 v25, v86, s8
	v_mul_lo_u32 v26, v88, s8
	v_mul_u32_u24_e32 v1, 0x210, v1
	v_or_b32_e32 v2, v2, v12
	s_mov_b64 s[12:13], 0x49a80000
	v_add_u32_e32 v134, 0x90, v131
	v_add_u32_e32 v137, 0x120, v131
	v_add_u32_e32 v140, 0x1b0, v131
	v_add_u32_e32 v162, s6, v19
	v_add_u32_e32 v166, s22, v19
	v_add_u32_e32 v167, s36, v19
	v_add_u32_e32 v168, s37, v19
	v_add_u32_e32 v169, s38, v19
	v_add_u32_e32 v170, s39, v19
	v_add_u32_e32 v171, s40, v19
	v_add_u32_e32 v172, s41, v19
	v_add_u32_e32 v174, s9, v8
	v_lshl_add_u64 v[92:93], v[2:3], 0, s[12:13]
	v_lshlrev_b64 v[94:95], 9, v[88:89]
	v_lshlrev_b64 v[96:97], 9, v[86:87]
	v_lshlrev_b64 v[98:99], 9, v[84:85]
	v_lshlrev_b64 v[100:101], 9, v[82:83]
	v_and_b32_e32 v239, 7, v238
	v_lshlrev_b32_e32 v175, 6, v239
	v_bfe_u32 v239, v238, 3, 1
	v_lshl_or_b32 v175, v239, 5, v175
	v_bfe_u32 v239, v238, 4, 1
	v_lshl_or_b32 v175, v239, 4, v175
	v_lshlrev_b32_e32 v102, 1, v4
	v_lshlrev_b32_e32 v186, 1, v6
	s_lshl_b32 s56, s15, 1
	v_add_u32_e32 v176, v9, v23
	v_add_u32_e32 v177, v9, v24
	v_add_u32_e32 v178, v9, v25
	v_add_u32_e32 v179, v9, v26
	v_add_u32_e32 v180, v11, v12
	v_add_u32_e32 v181, v10, v12
	v_add_u32_e32 v182, v14, v15
	v_add_u32_e32 v183, v17, v15
	v_add_u32_e32 v184, v20, v15
	v_add_u32_e32 v185, v13, v15
	v_add_u32_e32 v196, v5, v1
	v_add_u32_e32 v197, v16, v1
	v_readlane_b32 s11, v254, 13
	s_mov_b32 s12, s2
	v_readlane_b32 s13, v254, 12
	s_mov_b32 s14, s2
	v_bfe_u32 v244, v238, 4, 2
	v_lshlrev_b32_e32 v245, 4, v244
	v_and_b32_e32 v246, 1, v244
	v_lshrrev_b32_e32 v244, 1, v244
	v_lshlrev_b32_e32 v246, 8, v246
	v_lshl_add_u32 v246, v244, 7, v246
	v_sub_u32_e32 v246, v246, v245
	v_add_u32_e32 v182, v182, v246
	v_add_u32_e32 v183, v183, v246
	v_add_u32_e32 v184, v184, v246
	v_lshrrev_b32_e32 v245, 6, v238
	v_mul_u32_u24_e32 v245, 48, v245
	v_mul_u32_u24_e32 v246, 0xf0, v244
	v_sub_u32_e32 v246, v246, v245
	v_add_u32_e32 v196, v196, v246
	v_add_u32_e32 v197, v197, v246
	v_add_u32_e32 v197, 0x60, v197
	v_bfe_u32 v244, v238, 1, 1
	v_mul_u32_u24_e32 v246, 0xf0, v244
	v_sub_u32_e32 v246, v246, v245
	v_add_u32_e32 v149, v149, v246
	v_add_u32_e32 v151, v151, v246
	v_add_u32_e32 v161, v161, v246
	v_add_u32_e32 v163, v163, v246
	v_add_u32_e32 v246, 0x60, v246
	v_add_u32_e32 v152, v152, v246
	v_add_u32_e32 v153, v153, v246
	v_add_u32_e32 v164, v164, v246
	v_add_u32_e32 v165, v165, v246

.LBB0_440:
	s_setprio 0
	s_add_i32 s7, s63, 2
	s_cmp_ge_i32 s7, s55
	s_cbranch_scc1 .LBB0_490
	s_waitcnt vmcnt(0)
	v_readlane_b32 s4, v254, 32
	v_readlane_b32 s5, v254, 33
	s_waitcnt lgkmcnt(0)
	s_barrier
	s_and_saveexec_b64 s[16:17], s[4:5]
	s_cbranch_execz .LBB0_489
	v_readlane_b32 s4, v254, 14
	s_waitcnt vmcnt(0) expcnt(0) lgkmcnt(0)
	s_nop 0
	v_mov_b32_e32 v1, s4
	ds_read_b32 v4, v1
	v_readlane_b32 s4, v254, 15
	s_waitcnt lgkmcnt(0)
	v_cmp_ne_u32_e32 vcc, 0, v4
	v_mov_b32_e32 v1, s4
	ds_read_b32 v2, v1
	s_cbranch_vccnz .LBB0_457
	v_readlane_b32 s12, v252, 16
	v_readlane_b32 s13, v252, 17
	s_load_dwordx2 s[10:11], s[12:13], 0x4
	s_memrealtime s[18:19]
	s_waitcnt lgkmcnt(0)
	s_mul_i32 s10, s10, s85
	s_mul_i32 s10, s10, s11
	s_mov_b32 s11, 1
	s_branch .LBB0_445
